# attention tile loop: softmax trigger test shortened - the uniform flag is set by independent scalar moves, the branch follows the compare directly
# baseline (speedup 1.0000x reference)
; #define LAS __attribute__((address_space(3)))
; __device__ __forceinline__ void dattn_unit(LAS unsigned char* lds, int b, int h, int qb, const bf16* Q, const bf16* K, const bf16* V, bf16* YB, float lam, const float* subg, float oml, int tid) {
;     ...
;             AT_SOFTMAX(s0, 0, pA0, pB0);
;             AT_SOFTMAX(s1, 1, pA1, pB1);
; #pragma unroll
;             for (int cb = 0; cb < 4; ++cb) { const LAS bf16* vp = Vt + (32 * cb + ql) * 72 + 32 * sub + 4 * hi;
;                 const v2u a0 = *(const LAS v2u*)(vp), a1 = *(const LAS v2u*)(vp + 8), a2 = *(const LAS v2u*)(vp + 16), a3 = *(const LAS v2u*)(vp + 24);
;                 const v4u f0 = {a0.x, a0.y, a1.x, a1.y}, f1 = {a2.x, a2.y, a3.x, a3.y};
;                 o[0][cb] = __builtin_amdgcn_mfma_f32_32x32x16_bf16(__builtin_bit_cast(bf16x8, f0), pA0, o[0][cb], 0, 0, 0);
;                 o[1][cb] = __builtin_amdgcn_mfma_f32_32x32x16_bf16(__builtin_bit_cast(bf16x8, f0), pA1, o[1][cb], 0, 0, 0);
;                 o[0][cb] = __builtin_amdgcn_mfma_f32_32x32x16_bf16(__builtin_bit_cast(bf16x8, f1), pB0, o[0][cb], 0, 0, 0);
;                 o[1][cb] = __builtin_amdgcn_mfma_f32_32x32x16_bf16(__builtin_bit_cast(bf16x8, f1), pB1, o[1][cb], 0, 0, 0); }
.Lsm0_0:
	v_exp_f32_e32 v201, v144
	v_exp_f32_e32 v202, v145
	v_exp_f32_e32 v203, v146
	v_exp_f32_e32 v204, v147
	v_exp_f32_e32 v205, v148
	v_add_f32_e32 v144, v202, v201
	v_exp_f32_e32 v206, v149
	v_add_f32_e32 v144, v203, v144
	v_exp_f32_e32 v207, v150
	v_add_f32_e32 v144, v204, v144
	v_exp_f32_e32 v218, v151
	v_add_f32_e32 v144, v205, v144
	v_exp_f32_e32 v147, v152
	v_add_f32_e32 v144, v206, v144
	v_exp_f32_e32 v148, v153
	v_add_f32_e32 v144, v207, v144
	v_exp_f32_e32 v149, v154
	v_add_f32_e32 v144, v218, v144
	v_exp_f32_e32 v150, v155
	v_add_f32_e32 v144, v147, v144
	v_exp_f32_e32 v151, v156
	v_add_f32_e32 v144, v148, v144
	v_exp_f32_e32 v152, v157
	v_add_f32_e32 v144, v149, v144
	v_exp_f32_e32 v153, v158
	v_add_f32_e32 v144, v150, v144
	v_exp_f32_e32 v154, v159
	v_add_f32_e32 v144, v151, v144
	v_add_f32_e32 v144, v152, v144
	v_add_f32_e32 v144, v153, v144
	v_add_f32_e32 v145, v154, v144
	v_cmp_lt_f32_e32 vcc, s82, v145
	s_mov_b64 s[48:49], 0
	s_cbranch_vccz .LBB0_232
	s_mov_b64 s[48:49], -1
	v_max_f32_e32 v146, v204, v204
	v_max_f32_e32 v155, v203, v203
	v_max_f32_e32 v146, v155, v146
	v_max_f32_e32 v155, v218, v218
	v_max_f32_e32 v156, v207, v207
	v_max_f32_e32 v155, v156, v155
	v_max_f32_e32 v156, v148, v148
	v_max_f32_e32 v157, v147, v147
	v_max_f32_e32 v156, v157, v156
	v_max_f32_e32 v157, v150, v150
	v_max_f32_e32 v158, v149, v149
	v_max_f32_e32 v157, v158, v157
	v_max_f32_e32 v158, v154, v154
	v_max_f32_e32 v159, v153, v153
	v_max_f32_e32 v158, v159, v158
	v_max3_f32 v158, v151, v152, v158
	v_max3_f32 v146, v201, v202, v146
	v_max3_f32 v155, v205, v206, v155
	v_max3_f32 v156, v156, v157, v158
	v_max3_f32 v146, v146, v155, v156
	v_mov_b32_e32 v155, v146
	s_nop 1
	v_permlane32_swap_b32_e32 v146, v155
	v_max_f32_e32 v155, v155, v155
	v_max_f32_e32 v146, v146, v146
	v_max_f32_e32 v146, v146, v155
.LBB0_232:
	v_cvt_pk_bf16_f32 v224, v201, v202
	v_cvt_pk_bf16_f32 v225, v203, v204
	v_cvt_pk_bf16_f32 v226, v205, v206
	v_cvt_pk_bf16_f32 v227, v207, v218
	v_cvt_pk_bf16_f32 v148, v147, v148
	v_cvt_pk_bf16_f32 v149, v149, v150
	v_cvt_pk_bf16_f32 v150, v151, v152
	v_cvt_pk_bf16_f32 v151, v153, v154
	ds_read_b128 v[204:207], v219 offset:18464
	ds_read_b128 v[200:203], v219 offset:32288
	v_add_f32_e32 v179, v179, v145
	v_exp_f32_e32 v155, v128
	v_exp_f32_e32 v129, v129
	v_exp_f32_e32 v130, v130
	v_exp_f32_e32 v131, v131
	s_waitcnt lgkmcnt(2)
	v_mfma_f32_32x32x16_bf16 v[80:95], v[228:231], v[224:227], v[80:95]
	v_exp_f32_e32 v132, v132
	v_add_f32_e32 v128, v129, v155
	v_exp_f32_e32 v156, v133
	v_mfma_f32_32x32x16_bf16 v[80:95], v[232:235], v[148:151], v[80:95]
	v_add_f32_e32 v128, v130, v128
	v_exp_f32_e32 v157, v134
	v_add_f32_e32 v128, v131, v128
	v_exp_f32_e32 v158, v135
	v_mfma_f32_32x32x16_bf16 v[48:63], v[236:239], v[224:227], v[48:63]
	v_add_f32_e32 v128, v132, v128
	v_exp_f32_e32 v133, v136
	v_add_f32_e32 v128, v156, v128
	v_exp_f32_e32 v134, v137
	v_mfma_f32_32x32x16_bf16 v[48:63], v[240:243], v[148:151], v[48:63]
	v_add_f32_e32 v128, v157, v128
	v_exp_f32_e32 v135, v138
	v_add_f32_e32 v128, v158, v128
	v_exp_f32_e32 v136, v139
	v_mfma_f32_32x32x16_bf16 v[16:31], v[212:215], v[224:227], v[16:31]
	v_add_f32_e32 v128, v133, v128
	v_exp_f32_e32 v137, v140
	v_add_f32_e32 v128, v134, v128
	v_exp_f32_e32 v138, v141
	v_mfma_f32_32x32x16_bf16 v[112:127], v[220:223], v[224:227], v[112:127]
	v_add_f32_e32 v128, v135, v128
	v_exp_f32_e32 v139, v142
	v_add_f32_e32 v128, v136, v128
	v_exp_f32_e32 v140, v143
	s_waitcnt lgkmcnt(1)
	v_mfma_f32_32x32x16_bf16 v[112:127], v[204:207], v[148:151], v[112:127]
	v_add_f32_e32 v128, v137, v128
	v_add_f32_e32 v128, v138, v128
	v_add_f32_e32 v128, v139, v128
	v_add_f32_e32 v128, v140, v128
	s_waitcnt lgkmcnt(0)
	v_mfma_f32_32x32x16_bf16 v[16:31], v[200:203], v[148:151], v[16:31]
	v_cmp_lt_f32_e32 vcc, s82, v128
	s_mov_b64 s[46:47], 0
	s_cbranch_vccz .LBB0_234
	s_mov_b64 s[46:47], -1
	v_max_f32_e32 v141, v131, v131
	v_max_f32_e32 v142, v130, v130
	v_max_f32_e32 v141, v142, v141
	v_max_f32_e32 v142, v158, v158
	v_max_f32_e32 v143, v157, v157
	v_max_f32_e32 v142, v143, v142
	v_max_f32_e32 v143, v134, v134
	v_max_f32_e32 v144, v133, v133
	v_max_f32_e32 v143, v144, v143
	v_max_f32_e32 v144, v136, v136
	v_max_f32_e32 v159, v135, v135
	v_max_f32_e32 v144, v159, v144
	v_max_f32_e32 v159, v140, v140
	v_max_f32_e32 v147, v139, v139
	v_max_f32_e32 v159, v147, v159
	v_max3_f32 v159, v137, v138, v159
	v_max3_f32 v141, v155, v129, v141
	v_max3_f32 v142, v132, v156, v142
	v_max3_f32 v143, v143, v144, v159
	v_max3_f32 v141, v141, v142, v143
	v_mov_b32_e32 v142, v141
	s_nop 1
	v_permlane32_swap_b32_e32 v141, v142
	v_max_f32_e32 v142, v142, v142
	v_max_f32_e32 v141, v141, v141
	v_max_f32_e32 v144, v141, v142

; #define LAS __attribute__((address_space(3)))
; __device__ __forceinline__ void dattn_unit(LAS unsigned char* lds, int b, int h, int qb, const bf16* Q, const bf16* K, const bf16* V, bf16* YB, float lam, const float* subg, float oml, int tid) {
;     ...
;             AT_SOFTMAX(s0, 0, pA0, pB0);
;             AT_SOFTMAX(s1, 1, pA1, pB1);
; #pragma unroll
;             for (int cb = 0; cb < 4; ++cb) { const LAS bf16* vp = Vt + (32 * cb + ql) * 72 + 32 * sub + 4 * hi;
;                 const v2u a0 = *(const LAS v2u*)(vp), a1 = *(const LAS v2u*)(vp + 8), a2 = *(const LAS v2u*)(vp + 16), a3 = *(const LAS v2u*)(vp + 24);
;                 const v4u f0 = {a0.x, a0.y, a1.x, a1.y}, f1 = {a2.x, a2.y, a3.x, a3.y};
;                 o[0][cb] = __builtin_amdgcn_mfma_f32_32x32x16_bf16(__builtin_bit_cast(bf16x8, f0), pA0, o[0][cb], 0, 0, 0);
;                 o[1][cb] = __builtin_amdgcn_mfma_f32_32x32x16_bf16(__builtin_bit_cast(bf16x8, f0), pA1, o[1][cb], 0, 0, 0);
;                 o[0][cb] = __builtin_amdgcn_mfma_f32_32x32x16_bf16(__builtin_bit_cast(bf16x8, f1), pB0, o[0][cb], 0, 0, 0);
;                 o[1][cb] = __builtin_amdgcn_mfma_f32_32x32x16_bf16(__builtin_bit_cast(bf16x8, f1), pB1, o[1][cb], 0, 0, 0); }
.Lsm0_1:
	v_exp_f32_e32 v199, v144
	v_exp_f32_e32 v204, v145
	v_exp_f32_e32 v205, v146
	v_exp_f32_e32 v206, v147
	v_exp_f32_e32 v207, v148
	v_add_f32_e32 v144, v204, v199
	v_exp_f32_e32 v218, v149
	v_add_f32_e32 v144, v205, v144
	v_exp_f32_e32 v219, v150
	v_add_f32_e32 v144, v206, v144
	v_exp_f32_e32 v220, v151
	v_add_f32_e32 v144, v207, v144
	v_exp_f32_e32 v147, v152
	v_add_f32_e32 v144, v218, v144
	v_exp_f32_e32 v148, v153
	v_add_f32_e32 v144, v219, v144
	v_exp_f32_e32 v149, v154
	v_add_f32_e32 v144, v220, v144
	v_exp_f32_e32 v150, v155
	v_add_f32_e32 v144, v147, v144
	v_exp_f32_e32 v151, v156
	v_add_f32_e32 v144, v148, v144
	v_exp_f32_e32 v152, v157
	v_add_f32_e32 v144, v149, v144
	v_exp_f32_e32 v153, v158
	v_add_f32_e32 v144, v150, v144
	v_exp_f32_e32 v154, v159
	v_add_f32_e32 v144, v151, v144
	v_add_f32_e32 v144, v152, v144
	v_add_f32_e32 v144, v153, v144
	v_add_f32_e32 v145, v154, v144
	v_cmp_lt_f32_e32 vcc, s82, v145
	s_mov_b64 s[48:49], 0
	s_cbranch_vccz .LBB0_243
	s_mov_b64 s[48:49], -1
	v_max_f32_e32 v146, v206, v206
	v_max_f32_e32 v155, v205, v205
	v_max_f32_e32 v146, v155, v146
	v_max_f32_e32 v155, v220, v220
	v_max_f32_e32 v156, v219, v219
	v_max_f32_e32 v155, v156, v155
	v_max_f32_e32 v156, v148, v148
	v_max_f32_e32 v157, v147, v147
	v_max_f32_e32 v156, v157, v156
	v_max_f32_e32 v157, v150, v150
	v_max_f32_e32 v158, v149, v149
	v_max_f32_e32 v157, v158, v157
	v_max_f32_e32 v158, v154, v154
	v_max_f32_e32 v159, v153, v153
	v_max_f32_e32 v158, v159, v158
	v_max3_f32 v158, v151, v152, v158
	v_max3_f32 v146, v199, v204, v146
	v_max3_f32 v155, v207, v218, v155
	v_max3_f32 v156, v156, v157, v158
	v_max3_f32 v146, v146, v155, v156
	v_mov_b32_e32 v155, v146
	s_nop 1
	v_permlane32_swap_b32_e32 v146, v155
	v_max_f32_e32 v155, v155, v155
	v_max_f32_e32 v146, v146, v146
	v_max_f32_e32 v146, v146, v155
.LBB0_243:
	v_cvt_pk_bf16_f32 v205, v205, v206
	v_cvt_pk_bf16_f32 v206, v207, v218
	v_cvt_pk_bf16_f32 v207, v219, v220
	v_cvt_pk_bf16_f32 v204, v199, v204
	v_cvt_pk_bf16_f32 v148, v147, v148
	v_cvt_pk_bf16_f32 v149, v149, v150
	v_cvt_pk_bf16_f32 v150, v151, v152
	v_cvt_pk_bf16_f32 v151, v153, v154
	ds_read_b128 v[218:221], v243 offset:32352
	v_add_f32_e32 v179, v179, v145
	v_exp_f32_e32 v155, v128
	v_exp_f32_e32 v129, v129
	v_exp_f32_e32 v130, v130
	v_exp_f32_e32 v131, v131
	s_waitcnt lgkmcnt(1)
	v_mfma_f32_32x32x16_bf16 v[80:95], v[222:225], v[204:207], v[80:95]
	v_exp_f32_e32 v132, v132
	v_add_f32_e32 v128, v129, v155
	v_exp_f32_e32 v156, v133
	v_mfma_f32_32x32x16_bf16 v[80:95], v[226:229], v[148:151], v[80:95]
	v_add_f32_e32 v128, v130, v128
	v_exp_f32_e32 v157, v134
	v_add_f32_e32 v128, v131, v128
	v_exp_f32_e32 v158, v135
	v_mfma_f32_32x32x16_bf16 v[48:63], v[230:233], v[204:207], v[48:63]
	v_add_f32_e32 v128, v132, v128
	v_exp_f32_e32 v133, v136
	v_add_f32_e32 v128, v156, v128
	v_exp_f32_e32 v134, v137
	v_mfma_f32_32x32x16_bf16 v[48:63], v[234:237], v[148:151], v[48:63]
	v_add_f32_e32 v128, v157, v128
	v_exp_f32_e32 v135, v138
	v_add_f32_e32 v128, v158, v128
	v_exp_f32_e32 v136, v139
	v_mfma_f32_32x32x16_bf16 v[16:31], v[238:241], v[204:207], v[16:31]
	v_add_f32_e32 v128, v133, v128
	v_exp_f32_e32 v137, v140
	v_add_f32_e32 v128, v134, v128
	v_exp_f32_e32 v138, v141
	v_mfma_f32_32x32x16_bf16 v[112:127], v[212:215], v[204:207], v[112:127]
	v_add_f32_e32 v128, v135, v128
	v_exp_f32_e32 v139, v142
	v_add_f32_e32 v128, v136, v128
	v_exp_f32_e32 v140, v143
	v_mfma_f32_32x32x16_bf16 v[112:127], v[200:203], v[148:151], v[112:127]
	v_add_f32_e32 v128, v137, v128
	v_add_f32_e32 v128, v138, v128
	v_add_f32_e32 v128, v139, v128
	v_add_f32_e32 v128, v140, v128
	s_waitcnt lgkmcnt(0)
	v_mfma_f32_32x32x16_bf16 v[16:31], v[218:221], v[148:151], v[16:31]
	v_cmp_lt_f32_e32 vcc, s82, v128
	s_mov_b64 s[46:47], 0
	s_cbranch_vccz .LBB0_245
	s_mov_b64 s[46:47], -1
	v_max_f32_e32 v141, v131, v131
	v_max_f32_e32 v142, v130, v130
	v_max_f32_e32 v141, v142, v141
	v_max_f32_e32 v142, v158, v158
	v_max_f32_e32 v143, v157, v157
	v_max_f32_e32 v142, v143, v142
	v_max_f32_e32 v143, v134, v134
	v_max_f32_e32 v144, v133, v133
	v_max_f32_e32 v143, v144, v143
	v_max_f32_e32 v144, v136, v136
	v_max_f32_e32 v159, v135, v135
	v_max_f32_e32 v144, v159, v144
	v_max_f32_e32 v159, v140, v140
	v_max_f32_e32 v147, v139, v139
	v_max_f32_e32 v159, v147, v159
	v_max3_f32 v159, v137, v138, v159
	v_max3_f32 v141, v155, v129, v141
	v_max3_f32 v142, v132, v156, v142
	v_max3_f32 v143, v143, v144, v159
	v_max3_f32 v141, v141, v142, v143
	v_mov_b32_e32 v142, v141
	s_nop 1
	v_permlane32_swap_b32_e32 v141, v142
	v_max_f32_e32 v142, v142, v142
	v_max_f32_e32 v141, v141, v141
	v_max_f32_e32 v144, v141, v142
